# scan: group-norm statistics 16-lane reductions via DPP row ops instead of ds_bpermute (bit-identical), on top of attention edits
# speedup vs baseline: 1.0139x; 1.0001x over previous
; DI float bflo(unsigned w) { return __uint_as_float(w << 16); }
; DI float bfhi(unsigned w) { return __uint_as_float(w & 0xffff0000u); }
; DI void store8(bf16_t* p, f32x4 a, f32x4 b) { u32x4 w = {cvt_pk_bf16(a[0], a[1]), cvt_pk_bf16(a[2], a[3]), cvt_pk_bf16(b[0], b[1]), cvt_pk_bf16(b[2], b[3])}; *(u32x4*)p = w; }
; template <int FWD, class BarrierFn>
; DI void scan2_dir(const bf16_t* __restrict__ Qg, const bf16_t* __restrict__ Kg, bf16_t* Vg, bf16_t* Tg, bf16_t* TCB, float* stats, int b, int h, int sl, float lg, char* lds, const BarrierFn& gbar) {
;     ...
;         {
;             bf16_t* dst = (fin ? Vg : ((!FWD && step < 4) ? TCB - (size_t)TL * 2048 : Tg));
; #pragma unroll
;             for (int hf = 0; hf < 2; ++hf) {
;                 const float* sr = stg_r + hf * 32 * S2RS; const float xi = hf ? xi1 : xi0;
;                 f32x4 b0 = *(const f32x4*)sr * xi, b1 = *(const f32x4*)(sr + 4) * xi;
;                 if (fin) { const bf16x8 tvv = hf ? tv1 : tv0; const u32x4 ow = *reinterpret_cast<const u32x4*>(&tvv);
;                     b0[0] += bflo(ow[0]); b0[1] += bfhi(ow[0]); b0[2] += bflo(ow[1]); b0[3] += bfhi(ow[1]); b1[0] += bflo(ow[2]); b1[1] += bfhi(ow[2]); b1[2] += bflo(ow[3]); b1[3] += bfhi(ow[3]); }
;                 const size_t row = (size_t)(rb + srow + 32 * hf);
;                 store8(dst + row * 2048 + vcol + scp * 8, b0, b1);
;                 if (fin) {
;                     float sm = (b0[0] + b0[1]) + (b0[2] + b0[3]) + (b1[0] + b1[1]) + (b1[2] + b1[3]);
;                     float sq = (b0[0] * b0[0] + b0[1] * b0[1]) + (b0[2] * b0[2] + b0[3] * b0[3]) + (b1[0] * b1[0] + b1[1] * b1[1]) + (b1[2] * b1[2] + b1[3] * b1[3]);
; #pragma unroll
;                     for (int o_ = 1; o_ < 16; o_ <<= 1) { sm += __shfl_xor(sm, o_, 64); sq += __shfl_xor(sq, o_, 64); }
;                     if (scp == 0) { float* sp = stats + (row * 4 + h) * 2; unsafeAtomicAdd(sp, sm); unsafeAtomicAdd(sp + 1, sq); }
;                 }
.LBB0_366:
	s_and_b64 s[46:47], s[72:73], exec
	s_cselect_b32 s47, s97, s59
	s_cselect_b32 s46, s96, s58
	s_lshl_b32 s71, s63, 1
	s_add_u32 s46, s46, s71
	s_addc_u32 s47, s47, 0
	v_lshlrev_b32_e32 v180, 1, v154
	s_waitcnt vmcnt(1)
	v_lshl_add_u64 v[108:109], s[46:47], 0, v[180:181]
	v_lshlrev_b64 v[110:111], 12, v[166:167]
	v_lshl_add_u64 v[110:111], v[108:109], 0, v[110:111]
	s_and_b64 vcc, exec, s[0:1]
	v_cvt_pk_bf16_f32 v120, v118, v119
	v_cvt_pk_bf16_f32 v121, v116, v117
	v_cvt_pk_bf16_f32 v122, v114, v115
	v_cvt_pk_bf16_f32 v123, v112, v113
	global_store_dwordx4 v[110:111], v[120:123], off
	s_cbranch_vccnz .LBB0_370
	v_add_f32_e32 v110, v118, v119
	v_add_f32_e32 v111, v116, v117
	v_add_f32_e32 v110, v110, v111
	v_add_f32_e32 v111, v114, v115
	v_add_f32_e32 v110, v110, v111
	v_add_f32_e32 v111, v112, v113
	v_add_f32_e32 v110, v111, v110
	v_mul_f32_e32 v111, v119, v119
	v_mul_f32_e32 v117, v117, v117
	v_fmac_f32_e32 v111, v118, v118
	v_fmac_f32_e32 v117, v116, v116
	v_mul_f32_e32 v115, v115, v115
	v_add_f32_e32 v111, v111, v117
	v_fmac_f32_e32 v115, v114, v114
	v_mul_f32_e32 v113, v113, v113
	v_add_f32_e32 v111, v111, v115
	v_fmac_f32_e32 v113, v112, v112
	v_add_f32_e32 v111, v113, v111
	s_nop 1
	v_add_f32_dpp v110, v110, v110 quad_perm:[1,0,3,2] row_mask:0xf bank_mask:0xf
	v_add_f32_dpp v111, v111, v111 quad_perm:[1,0,3,2] row_mask:0xf bank_mask:0xf
	s_nop 1
	v_add_f32_dpp v110, v110, v110 quad_perm:[2,3,0,1] row_mask:0xf bank_mask:0xf
	v_add_f32_dpp v111, v111, v111 quad_perm:[2,3,0,1] row_mask:0xf bank_mask:0xf
	s_nop 1
	v_add_f32_dpp v110, v110, v110 row_half_mirror row_mask:0xf bank_mask:0xf
	v_add_f32_dpp v111, v111, v111 row_half_mirror row_mask:0xf bank_mask:0xf
	s_nop 1
	v_add_f32_dpp v112, v110, v110 row_mirror row_mask:0xf bank_mask:0xf
	v_add_f32_dpp v113, v111, v111 row_mirror row_mask:0xf bank_mask:0xf
	s_and_saveexec_b64 s[46:47], s[4:5]
	s_cbranch_execz .LBB0_369
	v_readlane_b32 s72, v254, 23
	s_waitcnt lgkmcnt(0)
	v_lshlrev_b64 v[110:111], 5, v[166:167]
	v_readlane_b32 s73, v254, 24
	s_nop 1
	v_lshl_add_u64 v[110:111], s[72:73], 0, v[110:111]
	global_atomic_add_f32 v[110:111], v112, off
	global_atomic_add_f32 v[110:111], v113, off offset:4

; DI float bflo(unsigned w) { return __uint_as_float(w << 16); }
; DI float bfhi(unsigned w) { return __uint_as_float(w & 0xffff0000u); }
; DI void store8(bf16_t* p, f32x4 a, f32x4 b) { u32x4 w = {cvt_pk_bf16(a[0], a[1]), cvt_pk_bf16(a[2], a[3]), cvt_pk_bf16(b[0], b[1]), cvt_pk_bf16(b[2], b[3])}; *(u32x4*)p = w; }
; template <int FWD, class BarrierFn>
; DI void scan2_dir(const bf16_t* __restrict__ Qg, const bf16_t* __restrict__ Kg, bf16_t* Vg, bf16_t* Tg, bf16_t* TCB, float* stats, int b, int h, int sl, float lg, char* lds, const BarrierFn& gbar) {
;     ...
;             for (int hf = 0; hf < 2; ++hf) {
;                 const float* sr = stg_r + hf * 32 * S2RS; const float xi = hf ? xi1 : xi0;
;                 f32x4 b0 = *(const f32x4*)sr * xi, b1 = *(const f32x4*)(sr + 4) * xi;
;                 if (fin) { const bf16x8 tvv = hf ? tv1 : tv0; const u32x4 ow = *reinterpret_cast<const u32x4*>(&tvv);
;                     b0[0] += bflo(ow[0]); b0[1] += bfhi(ow[0]); b0[2] += bflo(ow[1]); b0[3] += bfhi(ow[1]); b1[0] += bflo(ow[2]); b1[1] += bfhi(ow[2]); b1[2] += bflo(ow[3]); b1[3] += bfhi(ow[3]); }
;                 const size_t row = (size_t)(rb + srow + 32 * hf);
;                 store8(dst + row * 2048 + vcol + scp * 8, b0, b1);
;                 if (fin) {
;                     float sm = (b0[0] + b0[1]) + (b0[2] + b0[3]) + (b1[0] + b1[1]) + (b1[2] + b1[3]);
;                     float sq = (b0[0] * b0[0] + b0[1] * b0[1]) + (b0[2] * b0[2] + b0[3] * b0[3]) + (b1[0] * b1[0] + b1[1] * b1[1]) + (b1[2] * b1[2] + b1[3] * b1[3]);
; #pragma unroll
;                     for (int o_ = 1; o_ < 16; o_ <<= 1) { sm += __shfl_xor(sm, o_, 64); sq += __shfl_xor(sq, o_, 64); }
;                     if (scp == 0) { float* sp = stats + (row * 4 + h) * 2; unsafeAtomicAdd(sp, sm); unsafeAtomicAdd(sp + 1, sq); }
;                 }
.LBB0_372:
	s_waitcnt vmcnt(1)
	v_add_u32_e32 v104, 32, v166
	v_ashrrev_i32_e32 v105, 31, v104
	v_lshlrev_b64 v[106:107], 12, v[104:105]
	v_lshl_add_u64 v[118:119], v[108:109], 0, v[106:107]
	s_and_b64 vcc, exec, s[0:1]
	v_cvt_pk_bf16_f32 v106, v116, v117
	v_cvt_pk_bf16_f32 v107, v114, v115
	v_cvt_pk_bf16_f32 v108, v112, v113
	v_cvt_pk_bf16_f32 v109, v110, v111
	global_store_dwordx4 v[118:119], v[106:109], off
	s_cbranch_vccnz .LBB0_303
	s_nop 0
	v_add_f32_e32 v106, v116, v117
	v_add_f32_e32 v107, v114, v115
	v_add_f32_e32 v106, v106, v107
	v_add_f32_e32 v107, v112, v113
	v_add_f32_e32 v106, v106, v107
	v_add_f32_e32 v107, v110, v111
	v_add_f32_e32 v106, v107, v106
	v_mul_f32_e32 v107, v117, v117
	v_mul_f32_e32 v108, v115, v115
	v_fmac_f32_e32 v107, v116, v116
	v_fmac_f32_e32 v108, v114, v114
	v_add_f32_e32 v107, v107, v108
	v_mul_f32_e32 v108, v113, v113
	v_fmac_f32_e32 v108, v112, v112
	v_add_f32_e32 v107, v107, v108
	v_mul_f32_e32 v108, v111, v111
	v_fmac_f32_e32 v108, v110, v110
	v_add_f32_e32 v107, v108, v107
	s_nop 1
	v_add_f32_dpp v106, v106, v106 quad_perm:[1,0,3,2] row_mask:0xf bank_mask:0xf
	v_add_f32_dpp v107, v107, v107 quad_perm:[1,0,3,2] row_mask:0xf bank_mask:0xf
	s_nop 1
	v_add_f32_dpp v106, v106, v106 quad_perm:[2,3,0,1] row_mask:0xf bank_mask:0xf
	v_add_f32_dpp v107, v107, v107 quad_perm:[2,3,0,1] row_mask:0xf bank_mask:0xf
	s_nop 1
	v_add_f32_dpp v106, v106, v106 row_half_mirror row_mask:0xf bank_mask:0xf
	v_add_f32_dpp v107, v107, v107 row_half_mirror row_mask:0xf bank_mask:0xf
	s_nop 1
	v_add_f32_dpp v106, v106, v106 row_mirror row_mask:0xf bank_mask:0xf
	v_add_f32_dpp v107, v107, v107 row_mirror row_mask:0xf bank_mask:0xf
	s_and_saveexec_b64 s[0:1], s[4:5]
	s_cbranch_execz .LBB0_302
	v_readlane_b32 s46, v254, 23
	v_lshlrev_b64 v[104:105], 5, v[104:105]
	v_readlane_b32 s47, v254, 24
	s_waitcnt lgkmcnt(1)
	s_waitcnt lgkmcnt(0)
	v_lshl_add_u64 v[104:105], s[46:47], 0, v[104:105]
	global_atomic_add_f32 v[104:105], v106, off
	global_atomic_add_f32 v[104:105], v107, off offset:4
	s_branch .LBB0_302

; DI float bflo(unsigned w) { return __uint_as_float(w << 16); }
; DI float bfhi(unsigned w) { return __uint_as_float(w & 0xffff0000u); }
; DI void store8(bf16_t* p, f32x4 a, f32x4 b) { u32x4 w = {cvt_pk_bf16(a[0], a[1]), cvt_pk_bf16(a[2], a[3]), cvt_pk_bf16(b[0], b[1]), cvt_pk_bf16(b[2], b[3])}; *(u32x4*)p = w; }
; template <int FWD, class BarrierFn>
; DI void scan2_dir(const bf16_t* __restrict__ Qg, const bf16_t* __restrict__ Kg, bf16_t* Vg, bf16_t* Tg, bf16_t* TCB, float* stats, int b, int h, int sl, float lg, char* lds, const BarrierFn& gbar) {
;     ...
;         for (int p = tid; p < 4096; p += NTHREADS) { const int r = p >> 4, cp = p & 15; const size_t crow_ = (size_t)b * CTXL + r, row = TL + crow_;
;             const u32x4 fa = *(const u32x4*)(Tg + row * 2048 + vcol + cp * 8), fb = *(const u32x4*)(TCB + crow_ * 2048 + vcol + cp * 8);
;             f32x4 b0, b1;
;             b0[0] = bflo(fa[0]) + bflo(fb[0]); b0[1] = bfhi(fa[0]) + bfhi(fb[0]); b0[2] = bflo(fa[1]) + bflo(fb[1]); b0[3] = bfhi(fa[1]) + bfhi(fb[1]);
;             b1[0] = bflo(fa[2]) + bflo(fb[2]); b1[1] = bfhi(fa[2]) + bfhi(fb[2]); b1[2] = bflo(fa[3]) + bflo(fb[3]); b1[3] = bfhi(fa[3]) + bfhi(fb[3]);
;             store8(Vg + row * 2048 + vcol + cp * 8, b0, b1);
;             float sm = (b0[0] + b0[1]) + (b0[2] + b0[3]) + (b1[0] + b1[1]) + (b1[2] + b1[3]);
;             float sq = (b0[0] * b0[0] + b0[1] * b0[1]) + (b0[2] * b0[2] + b0[3] * b0[3]) + (b1[0] * b1[0] + b1[1] * b1[1]) + (b1[2] * b1[2] + b1[3] * b1[3]);
; #pragma unroll
;             for (int o_ = 1; o_ < 16; o_ <<= 1) { sm += __shfl_xor(sm, o_, 64); sq += __shfl_xor(sq, o_, 64); }
;             if (cp == 0) { float* sp = stats + (row * 4 + h) * 2; unsafeAtomicAdd(sp, sm); unsafeAtomicAdd(sp + 1, sq); }
;         }
.LBB0_378:
	v_ashrrev_i32_e32 v2, 4, v155
	v_readlane_b32 s8, v254, 30
	v_ashrrev_i32_e32 v3, 31, v2
	v_readlane_b32 s9, v254, 31
	s_nop 1
	v_lshl_add_u64 v[8:9], s[8:9], 0, v[2:3]
	s_mov_b64 s[8:9], 0x8000
	v_lshl_add_u64 v[2:3], v[8:9], 0, s[8:9]
	v_lshlrev_b64 v[12:13], 12, v[2:3]
	v_lshlrev_b64 v[8:9], 12, v[8:9]
	v_lshl_add_u64 v[4:5], v[146:147], 0, v[12:13]
	v_lshl_add_u64 v[8:9], v[0:1], 0, v[8:9]
	s_waitcnt lgkmcnt(0)
	global_load_dwordx4 v[4:7], v[4:5], off
	s_nop 0
	global_load_dwordx4 v[8:11], v[8:9], off
	s_waitcnt vmcnt(1)
	v_lshlrev_b32_e32 v15, 16, v4
	v_and_b32_e32 v4, 0xffff0000, v4
	s_waitcnt vmcnt(0)
	v_lshlrev_b32_e32 v14, 16, v8
	v_and_b32_e32 v8, 0xffff0000, v8
	v_add_f32_e32 v14, v14, v15
	v_add_f32_e32 v15, v8, v4
	v_lshlrev_b32_e32 v4, 16, v9
	v_lshlrev_b32_e32 v8, 16, v5
	v_add_f32_e32 v16, v4, v8
	v_and_b32_e32 v4, 0xffff0000, v9
	v_and_b32_e32 v5, 0xffff0000, v5
	v_add_f32_e32 v17, v4, v5
	v_lshlrev_b32_e32 v4, 16, v10
	v_lshlrev_b32_e32 v5, 16, v6
	v_add_f32_e32 v18, v4, v5
	v_and_b32_e32 v4, 0xffff0000, v10
	v_and_b32_e32 v5, 0xffff0000, v6
	v_add_f32_e32 v10, v4, v5
	v_lshlrev_b32_e32 v4, 16, v11
	v_lshlrev_b32_e32 v5, 16, v7
	v_add_f32_e32 v19, v4, v5
	v_and_b32_e32 v4, 0xffff0000, v11
	v_and_b32_e32 v5, 0xffff0000, v7
	v_add_f32_e32 v11, v4, v5
	v_lshl_add_u64 v[8:9], v[144:145], 0, v[12:13]
	v_cvt_pk_bf16_f32 v4, v14, v15
	v_cvt_pk_bf16_f32 v5, v16, v17
	v_cvt_pk_bf16_f32 v6, v18, v10
	v_cvt_pk_bf16_f32 v7, v19, v11
	global_store_dwordx4 v[8:9], v[4:7], off
	s_nop 1
	v_add_f32_e32 v4, v16, v17
	v_add_f32_e32 v5, v14, v15
	v_add_f32_e32 v4, v5, v4
	v_add_f32_e32 v5, v18, v10
	v_add_f32_e32 v4, v5, v4
	v_add_f32_e32 v5, v19, v11
	v_add_f32_e32 v4, v5, v4
	v_mul_f32_e32 v5, v16, v16
	v_mul_f32_e32 v6, v14, v14
	v_fmac_f32_e32 v5, v17, v17
	v_fmac_f32_e32 v6, v15, v15
	v_add_f32_e32 v5, v6, v5
	v_mul_f32_e32 v6, v18, v18
	v_fmac_f32_e32 v6, v10, v10
	v_add_f32_e32 v5, v6, v5
	v_mul_f32_e32 v6, v19, v19
	v_fmac_f32_e32 v6, v11, v11
	v_add_f32_e32 v5, v6, v5
	s_nop 1
	v_add_f32_dpp v4, v4, v4 quad_perm:[1,0,3,2] row_mask:0xf bank_mask:0xf
	v_add_f32_dpp v5, v5, v5 quad_perm:[1,0,3,2] row_mask:0xf bank_mask:0xf
	s_nop 1
	v_add_f32_dpp v4, v4, v4 quad_perm:[2,3,0,1] row_mask:0xf bank_mask:0xf
	v_add_f32_dpp v5, v5, v5 quad_perm:[2,3,0,1] row_mask:0xf bank_mask:0xf
	s_nop 1
	v_add_f32_dpp v4, v4, v4 row_half_mirror row_mask:0xf bank_mask:0xf
	v_add_f32_dpp v5, v5, v5 row_half_mirror row_mask:0xf bank_mask:0xf
	s_nop 1
	v_add_f32_dpp v4, v4, v4 row_mirror row_mask:0xf bank_mask:0xf
	v_add_f32_dpp v5, v5, v5 row_mirror row_mask:0xf bank_mask:0xf
	s_and_saveexec_b64 s[8:9], s[4:5]
	s_cbranch_execz .LBB0_377
	v_readlane_b32 s10, v254, 23
	v_lshlrev_b64 v[2:3], 5, v[2:3]
	v_readlane_b32 s11, v254, 24
	s_waitcnt lgkmcnt(1)
	s_waitcnt lgkmcnt(0)
	v_lshl_add_u64 v[2:3], s[10:11], 0, v[2:3]
	global_atomic_add_f32 v[2:3], v4, off
	global_atomic_add_f32 v[2:3], v5, off offset:4
	s_branch .LBB0_377

; DI float bflo(unsigned w) { return __uint_as_float(w << 16); }
; DI float bfhi(unsigned w) { return __uint_as_float(w & 0xffff0000u); }
; DI void store8(bf16_t* p, f32x4 a, f32x4 b) { u32x4 w = {cvt_pk_bf16(a[0], a[1]), cvt_pk_bf16(a[2], a[3]), cvt_pk_bf16(b[0], b[1]), cvt_pk_bf16(b[2], b[3])}; *(u32x4*)p = w; }
; template <int FWD, class BarrierFn>
; DI void scan2_dir(const bf16_t* __restrict__ Qg, const bf16_t* __restrict__ Kg, bf16_t* Vg, bf16_t* Tg, bf16_t* TCB, float* stats, int b, int h, int sl, float lg, char* lds, const BarrierFn& gbar) {
;     ...
;         {
;             bf16_t* dst = (fin ? Vg : ((!FWD && step < 4) ? TCB - (size_t)TL * 2048 : Tg));
; #pragma unroll
;             for (int hf = 0; hf < 2; ++hf) {
;                 const float* sr = stg_r + hf * 32 * S2RS; const float xi = hf ? xi1 : xi0;
;                 f32x4 b0 = *(const f32x4*)sr * xi, b1 = *(const f32x4*)(sr + 4) * xi;
;                 if (fin) { const bf16x8 tvv = hf ? tv1 : tv0; const u32x4 ow = *reinterpret_cast<const u32x4*>(&tvv);
;                     b0[0] += bflo(ow[0]); b0[1] += bfhi(ow[0]); b0[2] += bflo(ow[1]); b0[3] += bfhi(ow[1]); b1[0] += bflo(ow[2]); b1[1] += bfhi(ow[2]); b1[2] += bflo(ow[3]); b1[3] += bfhi(ow[3]); }
;                 const size_t row = (size_t)(rb + srow + 32 * hf);
;                 store8(dst + row * 2048 + vcol + scp * 8, b0, b1);
;                 if (fin) {
;                     float sm = (b0[0] + b0[1]) + (b0[2] + b0[3]) + (b1[0] + b1[1]) + (b1[2] + b1[3]);
;                     float sq = (b0[0] * b0[0] + b0[1] * b0[1]) + (b0[2] * b0[2] + b0[3] * b0[3]) + (b1[0] * b1[0] + b1[1] * b1[1]) + (b1[2] * b1[2] + b1[3] * b1[3]);
; #pragma unroll
;                     for (int o_ = 1; o_ < 16; o_ <<= 1) { sm += __shfl_xor(sm, o_, 64); sq += __shfl_xor(sq, o_, 64); }
;                     if (scp == 0) { float* sp = stats + (row * 4 + h) * 2; unsafeAtomicAdd(sp, sm); unsafeAtomicAdd(sp + 1, sq); }
;                 }
.LBB0_447:
	s_and_b64 s[46:47], s[70:71], exec
	v_readlane_b32 s46, v254, 32
	s_cselect_b32 s70, s46, s58
	v_readlane_b32 s46, v254, 33
	s_cselect_b32 s71, s46, s59
	s_and_b64 s[46:47], s[72:73], exec
	s_cselect_b32 s47, s97, s71
	s_cselect_b32 s46, s96, s70
	s_lshl_b32 s70, s63, 1
	s_add_u32 s46, s46, s70
	s_addc_u32 s47, s47, 0
	s_waitcnt vmcnt(1)
	v_lshl_add_u64 v[108:109], s[46:47], 0, v[180:181]
	v_lshlrev_b64 v[110:111], 12, v[164:165]
	v_lshl_add_u64 v[110:111], v[108:109], 0, v[110:111]
	s_and_b64 vcc, exec, s[0:1]
	v_cvt_pk_bf16_f32 v120, v118, v119
	v_cvt_pk_bf16_f32 v121, v116, v117
	v_cvt_pk_bf16_f32 v122, v114, v115
	v_cvt_pk_bf16_f32 v123, v112, v113
	global_store_dwordx4 v[110:111], v[120:123], off
	s_cbranch_vccnz .LBB0_451
	v_add_f32_e32 v110, v118, v119
	v_add_f32_e32 v111, v116, v117
	v_add_f32_e32 v110, v110, v111
	v_add_f32_e32 v111, v114, v115
	v_add_f32_e32 v110, v110, v111
	v_add_f32_e32 v111, v112, v113
	v_add_f32_e32 v110, v111, v110
	v_mul_f32_e32 v111, v119, v119
	v_mul_f32_e32 v117, v117, v117
	v_fmac_f32_e32 v111, v118, v118
	v_fmac_f32_e32 v117, v116, v116
	v_mul_f32_e32 v115, v115, v115
	v_add_f32_e32 v111, v111, v117
	v_fmac_f32_e32 v115, v114, v114
	v_mul_f32_e32 v113, v113, v113
	v_add_f32_e32 v111, v111, v115
	v_fmac_f32_e32 v113, v112, v112
	v_add_f32_e32 v111, v113, v111
	s_nop 1
	v_add_f32_dpp v110, v110, v110 quad_perm:[1,0,3,2] row_mask:0xf bank_mask:0xf
	v_add_f32_dpp v111, v111, v111 quad_perm:[1,0,3,2] row_mask:0xf bank_mask:0xf
	s_nop 1
	v_add_f32_dpp v110, v110, v110 quad_perm:[2,3,0,1] row_mask:0xf bank_mask:0xf
	v_add_f32_dpp v111, v111, v111 quad_perm:[2,3,0,1] row_mask:0xf bank_mask:0xf
	s_nop 1
	v_add_f32_dpp v110, v110, v110 row_half_mirror row_mask:0xf bank_mask:0xf
	v_add_f32_dpp v111, v111, v111 row_half_mirror row_mask:0xf bank_mask:0xf
	s_nop 1
	v_add_f32_dpp v112, v110, v110 row_mirror row_mask:0xf bank_mask:0xf
	v_add_f32_dpp v113, v111, v111 row_mirror row_mask:0xf bank_mask:0xf
	s_and_saveexec_b64 s[46:47], s[4:5]
	s_cbranch_execz .LBB0_450
	v_readlane_b32 s70, v254, 23
	s_waitcnt lgkmcnt(0)
	v_lshlrev_b64 v[110:111], 5, v[164:165]
	v_readlane_b32 s71, v254, 24
	s_nop 1
	v_lshl_add_u64 v[110:111], s[70:71], 0, v[110:111]
	global_atomic_add_f32 v[110:111], v112, off
	global_atomic_add_f32 v[110:111], v113, off offset:4

; DI float bflo(unsigned w) { return __uint_as_float(w << 16); }
; DI float bfhi(unsigned w) { return __uint_as_float(w & 0xffff0000u); }
; DI void store8(bf16_t* p, f32x4 a, f32x4 b) { u32x4 w = {cvt_pk_bf16(a[0], a[1]), cvt_pk_bf16(a[2], a[3]), cvt_pk_bf16(b[0], b[1]), cvt_pk_bf16(b[2], b[3])}; *(u32x4*)p = w; }
; template <int FWD, class BarrierFn>
; DI void scan2_dir(const bf16_t* __restrict__ Qg, const bf16_t* __restrict__ Kg, bf16_t* Vg, bf16_t* Tg, bf16_t* TCB, float* stats, int b, int h, int sl, float lg, char* lds, const BarrierFn& gbar) {
;     ...
;             for (int hf = 0; hf < 2; ++hf) {
;                 const float* sr = stg_r + hf * 32 * S2RS; const float xi = hf ? xi1 : xi0;
;                 f32x4 b0 = *(const f32x4*)sr * xi, b1 = *(const f32x4*)(sr + 4) * xi;
;                 if (fin) { const bf16x8 tvv = hf ? tv1 : tv0; const u32x4 ow = *reinterpret_cast<const u32x4*>(&tvv);
;                     b0[0] += bflo(ow[0]); b0[1] += bfhi(ow[0]); b0[2] += bflo(ow[1]); b0[3] += bfhi(ow[1]); b1[0] += bflo(ow[2]); b1[1] += bfhi(ow[2]); b1[2] += bflo(ow[3]); b1[3] += bfhi(ow[3]); }
;                 const size_t row = (size_t)(rb + srow + 32 * hf);
;                 store8(dst + row * 2048 + vcol + scp * 8, b0, b1);
;                 if (fin) {
;                     float sm = (b0[0] + b0[1]) + (b0[2] + b0[3]) + (b1[0] + b1[1]) + (b1[2] + b1[3]);
;                     float sq = (b0[0] * b0[0] + b0[1] * b0[1]) + (b0[2] * b0[2] + b0[3] * b0[3]) + (b1[0] * b1[0] + b1[1] * b1[1]) + (b1[2] * b1[2] + b1[3] * b1[3]);
; #pragma unroll
;                     for (int o_ = 1; o_ < 16; o_ <<= 1) { sm += __shfl_xor(sm, o_, 64); sq += __shfl_xor(sq, o_, 64); }
;                     if (scp == 0) { float* sp = stats + (row * 4 + h) * 2; unsafeAtomicAdd(sp, sm); unsafeAtomicAdd(sp + 1, sq); }
;                 }
.LBB0_453:
	s_waitcnt vmcnt(1)
	v_add_u32_e32 v104, 32, v164
	v_ashrrev_i32_e32 v105, 31, v104
	v_lshlrev_b64 v[106:107], 12, v[104:105]
	v_lshl_add_u64 v[118:119], v[108:109], 0, v[106:107]
	s_and_b64 vcc, exec, s[0:1]
	v_cvt_pk_bf16_f32 v106, v116, v117
	v_cvt_pk_bf16_f32 v107, v114, v115
	v_cvt_pk_bf16_f32 v108, v112, v113
	v_cvt_pk_bf16_f32 v109, v110, v111
	global_store_dwordx4 v[118:119], v[106:109], off
	s_cbranch_vccnz .LBB0_384
	s_nop 0
	v_add_f32_e32 v106, v116, v117
	v_add_f32_e32 v107, v114, v115
	v_add_f32_e32 v106, v106, v107
	v_add_f32_e32 v107, v112, v113
	v_add_f32_e32 v106, v106, v107
	v_add_f32_e32 v107, v110, v111
	v_add_f32_e32 v106, v107, v106
	v_mul_f32_e32 v107, v117, v117
	v_mul_f32_e32 v108, v115, v115
	v_fmac_f32_e32 v107, v116, v116
	v_fmac_f32_e32 v108, v114, v114
	v_add_f32_e32 v107, v107, v108
	v_mul_f32_e32 v108, v113, v113
	v_fmac_f32_e32 v108, v112, v112
	v_add_f32_e32 v107, v107, v108
	v_mul_f32_e32 v108, v111, v111
	v_fmac_f32_e32 v108, v110, v110
	v_add_f32_e32 v107, v108, v107
	s_nop 1
	v_add_f32_dpp v106, v106, v106 quad_perm:[1,0,3,2] row_mask:0xf bank_mask:0xf
	v_add_f32_dpp v107, v107, v107 quad_perm:[1,0,3,2] row_mask:0xf bank_mask:0xf
	s_nop 1
	v_add_f32_dpp v106, v106, v106 quad_perm:[2,3,0,1] row_mask:0xf bank_mask:0xf
	v_add_f32_dpp v107, v107, v107 quad_perm:[2,3,0,1] row_mask:0xf bank_mask:0xf
	s_nop 1
	v_add_f32_dpp v106, v106, v106 row_half_mirror row_mask:0xf bank_mask:0xf
	v_add_f32_dpp v107, v107, v107 row_half_mirror row_mask:0xf bank_mask:0xf
	s_nop 1
	v_add_f32_dpp v106, v106, v106 row_mirror row_mask:0xf bank_mask:0xf
	v_add_f32_dpp v107, v107, v107 row_mirror row_mask:0xf bank_mask:0xf
	s_and_saveexec_b64 s[0:1], s[4:5]
	s_cbranch_execz .LBB0_383
	v_readlane_b32 s46, v254, 23
	v_lshlrev_b64 v[104:105], 5, v[104:105]
	v_readlane_b32 s47, v254, 24
	s_waitcnt lgkmcnt(1)
	s_waitcnt lgkmcnt(0)
	v_lshl_add_u64 v[104:105], s[46:47], 0, v[104:105]
	global_atomic_add_f32 v[104:105], v106, off
	global_atomic_add_f32 v[104:105], v107, off offset:4
	s_branch .LBB0_383
